# ping-pong attention, staged tile written to LDS later in the MFMA segment
# speedup vs baseline: 1.0396x; 1.0098x over previous
.Lpp_enter:
.LBB0_1013:
	s_waitcnt lgkmcnt(1)
	v_mfma_f32_32x32x16_bf16 v[50:65], v[226:229], v[170:173], v[50:65]
	ds_read_b128 v[246:249], v235 offset:32
	v_mfma_f32_32x32x16_bf16 v[16:31], v[226:229], v[174:177], v[16:31]
	s_add_i32 s44, s4, 1
	s_and_b32 s43, s44, 1
	s_mul_i32 s43, s43, 0x2400
	s_waitcnt lgkmcnt(1)
	v_mfma_f32_32x32x16_bf16 v[34:49], v[230:233], v[170:173], v[34:49]
	ds_read_b128 v[226:229], v235 offset:4640
	v_add_u32_e32 v198, s43, v203
	v_add_u32_e32 v199, s42, v203
	v_mfma_f32_32x32x16_bf16 v[0:15], v[230:233], v[174:177], v[0:15]
	s_add_i32 s16, s4, 2
	s_min_u32 s16, s16, 63
	s_waitcnt lgkmcnt(1)
	v_mfma_f32_32x32x16_bf16 v[50:65], v[246:249], v[166:169], v[50:65]
	ds_read_b128 v[230:233], v235 offset:64
	v_mfma_f32_32x32x16_bf16 v[16:31], v[246:249], v[162:165], v[16:31]
	s_waitcnt lgkmcnt(1)
	v_mfma_f32_32x32x16_bf16 v[34:49], v[226:229], v[166:169], v[34:49]
	ds_read_b128 v[246:249], v235 offset:4672
	v_mfma_f32_32x32x16_bf16 v[0:15], v[226:229], v[162:165], v[0:15]
	s_waitcnt lgkmcnt(1)
	v_mfma_f32_32x32x16_bf16 v[50:65], v[230:233], v[186:189], v[50:65]
	ds_read_b128 v[226:229], v235 offset:96
	v_mfma_f32_32x32x16_bf16 v[16:31], v[230:233], v[218:221], v[16:31]
	s_waitcnt lgkmcnt(1)
	v_mfma_f32_32x32x16_bf16 v[34:49], v[246:249], v[186:189], v[34:49]
	ds_read_b128 v[230:233], v235 offset:4704
	v_mfma_f32_32x32x16_bf16 v[0:15], v[246:249], v[218:221], v[0:15]
	s_waitcnt lgkmcnt(1)
	v_mfma_f32_32x32x16_bf16 v[50:65], v[226:229], v[190:193], v[50:65]
	ds_read_b128 v[246:249], v234
	v_mfma_f32_32x32x16_bf16 v[16:31], v[226:229], v[222:225], v[16:31]
	s_waitcnt lgkmcnt(1)
	v_mfma_f32_32x32x16_bf16 v[34:49], v[230:233], v[190:193], v[34:49]
	ds_read_b128 v[226:229], v234 offset:32
	v_mfma_f32_32x32x16_bf16 v[0:15], v[230:233], v[222:225], v[0:15]
	s_waitcnt lgkmcnt(1)
	v_mfma_f32_32x32x16_bf16 v[114:129], v[246:249], v[130:133], 0
	ds_read_b128 v[230:233], v234 offset:64
	v_mfma_f32_32x32x16_bf16 v[98:113], v[246:249], v[146:149], 0
	s_waitcnt lgkmcnt(1)
	v_mfma_f32_32x32x16_bf16 v[114:129], v[226:229], v[134:137], v[114:129]
	ds_read_b128 v[246:249], v234 offset:96
	s_waitcnt vmcnt(0)
	ds_write_b128 v199, v[178:181]
	v_mfma_f32_32x32x16_bf16 v[98:113], v[226:229], v[150:153], v[98:113]
	s_waitcnt lgkmcnt(2)
	v_mfma_f32_32x32x16_bf16 v[114:129], v[230:233], v[138:141], v[114:129]
	ds_read_b128 v[226:229], v234 offset:4608
	ds_write_b128 v198, v[182:185]
	v_mfma_f32_32x32x16_bf16 v[98:113], v[230:233], v[154:157], v[98:113]
	s_waitcnt lgkmcnt(3)
	v_mfma_f32_32x32x16_bf16 v[114:129], v[246:249], v[142:145], v[114:129]
	ds_read_b128 v[230:233], v234 offset:4640
	s_lshl_b64 s[6:7], s[16:17], 13
	v_lshl_add_u64 v[182:183], v[212:213], 0, s[6:7]
	v_mfma_f32_32x32x16_bf16 v[98:113], v[246:249], v[158:161], v[98:113]
	global_load_dwordx4 v[182:185], v[182:183], off
	s_lshl_b64 s[6:7], s[16:17], 7
	s_waitcnt lgkmcnt(2)
	v_mfma_f32_32x32x16_bf16 v[82:97], v[226:229], v[130:133], 0
	ds_read_b128 v[246:249], v234 offset:4672
	v_lshl_add_u64 v[178:179], v[214:215], 0, s[6:7]
	v_mfma_f32_32x32x16_bf16 v[66:81], v[226:229], v[146:149], 0
	global_load_dwordx4 v[178:181], v[178:179], off
	s_waitcnt lgkmcnt(1)
	v_mfma_f32_32x32x16_bf16 v[82:97], v[230:233], v[134:137], v[82:97]
	ds_read_b128 v[226:229], v234 offset:4704
	v_mfma_f32_32x32x16_bf16 v[66:81], v[230:233], v[150:153], v[66:81]
	s_waitcnt lgkmcnt(1)
	v_mfma_f32_32x32x16_bf16 v[82:97], v[246:249], v[138:141], v[82:97]
	v_mfma_f32_32x32x16_bf16 v[66:81], v[246:249], v[154:157], v[66:81]
	s_waitcnt lgkmcnt(0)
	v_mfma_f32_32x32x16_bf16 v[82:97], v[226:229], v[142:145], v[82:97]
	v_mfma_f32_32x32x16_bf16 v[66:81], v[226:229], v[158:161], v[66:81]
	s_barrier
	v_exp_f32_e32 v114, v114
	v_exp_f32_e32 v115, v115
	v_exp_f32_e32 v116, v116
	v_exp_f32_e32 v117, v117
	v_exp_f32_e32 v118, v118
	v_exp_f32_e32 v119, v119
	v_exp_f32_e32 v120, v120
	v_exp_f32_e32 v121, v121
	v_cvt_pk_bf16_f32 v170, v114, v115
	v_add_f32_e32 v114, v114, v115
	v_exp_f32_e32 v122, v122
	v_exp_f32_e32 v123, v123
	v_cvt_pk_bf16_f32 v171, v116, v117
	v_add_f32_e32 v116, v116, v117
	v_add_f32_e32 v217, v217, v114
	v_exp_f32_e32 v124, v124
	v_exp_f32_e32 v125, v125
	v_cvt_pk_bf16_f32 v172, v118, v119
	v_add_f32_e32 v118, v118, v119
	v_add_f32_e32 v217, v217, v116
	v_exp_f32_e32 v126, v126
	v_exp_f32_e32 v127, v127
	v_cvt_pk_bf16_f32 v173, v120, v121
	v_add_f32_e32 v120, v120, v121
	v_add_f32_e32 v217, v217, v118
	v_exp_f32_e32 v128, v128
	v_exp_f32_e32 v129, v129
	v_cvt_pk_bf16_f32 v166, v122, v123
	v_add_f32_e32 v122, v122, v123
	v_add_f32_e32 v217, v217, v120
	v_exp_f32_e32 v98, v98
	v_exp_f32_e32 v99, v99
	v_cvt_pk_bf16_f32 v167, v124, v125
	v_add_f32_e32 v124, v124, v125
	v_add_f32_e32 v217, v217, v122
	v_exp_f32_e32 v100, v100
	v_exp_f32_e32 v101, v101
	v_cvt_pk_bf16_f32 v168, v126, v127
	v_add_f32_e32 v126, v126, v127
	v_add_f32_e32 v217, v217, v124
	v_exp_f32_e32 v102, v102
	v_exp_f32_e32 v103, v103
	v_cvt_pk_bf16_f32 v169, v128, v129
	v_add_f32_e32 v128, v128, v129
	v_add_f32_e32 v217, v217, v126
	v_exp_f32_e32 v104, v104
	v_exp_f32_e32 v105, v105
	v_cvt_pk_bf16_f32 v174, v98, v99
	v_add_f32_e32 v98, v98, v99
	v_add_f32_e32 v217, v217, v128
	v_exp_f32_e32 v106, v106
	v_exp_f32_e32 v107, v107
	v_cvt_pk_bf16_f32 v175, v100, v101
	v_add_f32_e32 v100, v100, v101
	v_add_f32_e32 v216, v216, v98
	v_exp_f32_e32 v108, v108
	v_exp_f32_e32 v109, v109
	v_cvt_pk_bf16_f32 v176, v102, v103
	v_add_f32_e32 v102, v102, v103
	v_add_f32_e32 v216, v216, v100
	v_exp_f32_e32 v110, v110
	v_exp_f32_e32 v111, v111
	v_cvt_pk_bf16_f32 v177, v104, v105
	v_add_f32_e32 v104, v104, v105
	v_add_f32_e32 v216, v216, v102
	v_exp_f32_e32 v112, v112
	v_exp_f32_e32 v113, v113
	v_cvt_pk_bf16_f32 v162, v106, v107
	v_add_f32_e32 v106, v106, v107
	v_add_f32_e32 v216, v216, v104
	v_cvt_pk_bf16_f32 v163, v108, v109
	v_add_f32_e32 v108, v108, v109
	v_add_f32_e32 v216, v216, v106
	v_cvt_pk_bf16_f32 v164, v110, v111
	v_add_f32_e32 v110, v110, v111
	v_add_f32_e32 v216, v216, v108
	v_cvt_pk_bf16_f32 v165, v112, v113
	v_add_f32_e32 v112, v112, v113
	v_add_f32_e32 v216, v216, v110
	v_add_f32_e32 v216, v216, v112
	v_exp_f32_e32 v82, v82
	v_exp_f32_e32 v83, v83
	v_exp_f32_e32 v84, v84
	v_exp_f32_e32 v85, v85
	v_exp_f32_e32 v86, v86
	v_exp_f32_e32 v87, v87
	v_exp_f32_e32 v88, v88
	v_exp_f32_e32 v89, v89
	v_cvt_pk_bf16_f32 v186, v82, v83
	v_add_f32_e32 v82, v82, v83
	v_exp_f32_e32 v90, v90
	v_exp_f32_e32 v91, v91
	v_cvt_pk_bf16_f32 v187, v84, v85
	v_add_f32_e32 v84, v84, v85
	v_add_f32_e32 v217, v217, v82
	v_exp_f32_e32 v92, v92
	v_exp_f32_e32 v93, v93
	v_cvt_pk_bf16_f32 v188, v86, v87
	v_add_f32_e32 v86, v86, v87
	v_add_f32_e32 v217, v217, v84
	v_exp_f32_e32 v94, v94
	v_exp_f32_e32 v95, v95
	v_cvt_pk_bf16_f32 v189, v88, v89
	v_add_f32_e32 v88, v88, v89
	v_add_f32_e32 v217, v217, v86
	v_exp_f32_e32 v96, v96
	v_exp_f32_e32 v97, v97
	v_cvt_pk_bf16_f32 v190, v90, v91
	v_add_f32_e32 v90, v90, v91
	v_add_f32_e32 v217, v217, v88
	v_exp_f32_e32 v66, v66
	v_exp_f32_e32 v67, v67
	v_cvt_pk_bf16_f32 v191, v92, v93
	v_add_f32_e32 v92, v92, v93
	v_add_f32_e32 v217, v217, v90
	v_exp_f32_e32 v68, v68
	v_exp_f32_e32 v69, v69
	v_cvt_pk_bf16_f32 v192, v94, v95
	v_add_f32_e32 v94, v94, v95
	v_add_f32_e32 v217, v217, v92
	v_exp_f32_e32 v70, v70
	v_exp_f32_e32 v71, v71
	v_cvt_pk_bf16_f32 v193, v96, v97
	v_add_f32_e32 v96, v96, v97
	v_add_f32_e32 v217, v217, v94
	v_exp_f32_e32 v72, v72
	v_exp_f32_e32 v73, v73
	v_cvt_pk_bf16_f32 v218, v66, v67
	v_add_f32_e32 v66, v66, v67
	v_add_f32_e32 v217, v217, v96
	v_exp_f32_e32 v74, v74
	v_exp_f32_e32 v75, v75
	v_cvt_pk_bf16_f32 v219, v68, v69
	v_add_f32_e32 v68, v68, v69
	v_add_f32_e32 v216, v216, v66
	v_exp_f32_e32 v76, v76
	v_exp_f32_e32 v77, v77
	v_cvt_pk_bf16_f32 v220, v70, v71
	v_add_f32_e32 v70, v70, v71
	v_add_f32_e32 v216, v216, v68
	v_exp_f32_e32 v78, v78
	v_exp_f32_e32 v79, v79
	v_cvt_pk_bf16_f32 v221, v72, v73
	v_add_f32_e32 v72, v72, v73
	v_add_f32_e32 v216, v216, v70
	v_exp_f32_e32 v80, v80
	v_exp_f32_e32 v81, v81
	v_cvt_pk_bf16_f32 v222, v74, v75
	v_add_f32_e32 v74, v74, v75
	v_add_f32_e32 v216, v216, v72
	v_cvt_pk_bf16_f32 v223, v76, v77
	v_add_f32_e32 v76, v76, v77
	v_add_f32_e32 v216, v216, v74
	v_cvt_pk_bf16_f32 v224, v78, v79
	v_add_f32_e32 v78, v78, v79
	v_add_f32_e32 v216, v216, v76
	v_cvt_pk_bf16_f32 v225, v80, v81
	v_add_f32_e32 v80, v80, v81
	v_add_f32_e32 v216, v216, v78
	v_add_f32_e32 v216, v216, v80
	v_add_u32_e32 v235, s41, v32
	v_add_u32_e32 v234, s43, v245
	ds_read_b128 v[226:229], v235
	ds_read_b128 v[230:233], v235 offset:4608
	s_waitcnt lgkmcnt(2)
	s_mov_b32 s6, s5
	s_mov_b32 s5, s41
	s_mov_b32 s41, s42
	s_mov_b32 s42, s6
	s_mov_b32 s4, s44
	s_cmp_eq_u32 s44, 63
	s_barrier
	s_cbranch_scc0 .LBB0_1013
	s_waitcnt lgkmcnt(1)
	v_mfma_f32_32x32x16_bf16 v[50:65], v[226:229], v[170:173], v[50:65]
	ds_read_b128 v[246:249], v235 offset:32
	v_mfma_f32_32x32x16_bf16 v[16:31], v[226:229], v[174:177], v[16:31]
	s_waitcnt lgkmcnt(1)
	v_mfma_f32_32x32x16_bf16 v[34:49], v[230:233], v[170:173], v[34:49]
	ds_read_b128 v[226:229], v235 offset:4640
	v_mfma_f32_32x32x16_bf16 v[0:15], v[230:233], v[174:177], v[0:15]
	s_waitcnt lgkmcnt(1)
	v_mfma_f32_32x32x16_bf16 v[50:65], v[246:249], v[166:169], v[50:65]
	ds_read_b128 v[230:233], v235 offset:64
	v_mfma_f32_32x32x16_bf16 v[16:31], v[246:249], v[162:165], v[16:31]
	s_waitcnt lgkmcnt(1)
	v_mfma_f32_32x32x16_bf16 v[34:49], v[226:229], v[166:169], v[34:49]
	ds_read_b128 v[246:249], v235 offset:4672
	v_mfma_f32_32x32x16_bf16 v[0:15], v[226:229], v[162:165], v[0:15]
	s_waitcnt lgkmcnt(1)
	v_mfma_f32_32x32x16_bf16 v[50:65], v[230:233], v[186:189], v[50:65]
	ds_read_b128 v[226:229], v235 offset:96
	v_mfma_f32_32x32x16_bf16 v[16:31], v[230:233], v[218:221], v[16:31]
	s_waitcnt lgkmcnt(1)
	v_mfma_f32_32x32x16_bf16 v[34:49], v[246:249], v[186:189], v[34:49]
	ds_read_b128 v[230:233], v235 offset:4704
	v_mfma_f32_32x32x16_bf16 v[0:15], v[246:249], v[218:221], v[0:15]
	s_waitcnt lgkmcnt(1)
	v_mfma_f32_32x32x16_bf16 v[50:65], v[226:229], v[190:193], v[50:65]
	ds_read_b128 v[246:249], v234
	v_mfma_f32_32x32x16_bf16 v[16:31], v[226:229], v[222:225], v[16:31]
	s_waitcnt lgkmcnt(1)
	v_mfma_f32_32x32x16_bf16 v[34:49], v[230:233], v[190:193], v[34:49]
	ds_read_b128 v[226:229], v234 offset:32
	v_mfma_f32_32x32x16_bf16 v[0:15], v[230:233], v[222:225], v[0:15]
	s_waitcnt lgkmcnt(1)
	v_mfma_f32_32x32x16_bf16 v[114:129], v[246:249], v[130:133], 0
	ds_read_b128 v[230:233], v234 offset:64
	v_mfma_f32_32x32x16_bf16 v[98:113], v[246:249], v[146:149], 0
	s_waitcnt lgkmcnt(1)
	v_mfma_f32_32x32x16_bf16 v[114:129], v[226:229], v[134:137], v[114:129]
	ds_read_b128 v[246:249], v234 offset:96
	v_mfma_f32_32x32x16_bf16 v[98:113], v[226:229], v[150:153], v[98:113]
	s_waitcnt lgkmcnt(1)
	v_mfma_f32_32x32x16_bf16 v[114:129], v[230:233], v[138:141], v[114:129]
	ds_read_b128 v[226:229], v234 offset:4608
	v_mfma_f32_32x32x16_bf16 v[98:113], v[230:233], v[154:157], v[98:113]
	s_waitcnt lgkmcnt(1)
	v_mfma_f32_32x32x16_bf16 v[114:129], v[246:249], v[142:145], v[114:129]
	ds_read_b128 v[230:233], v234 offset:4640
	v_mfma_f32_32x32x16_bf16 v[98:113], v[246:249], v[158:161], v[98:113]
	s_waitcnt lgkmcnt(1)
	v_mfma_f32_32x32x16_bf16 v[82:97], v[226:229], v[130:133], 0
	ds_read_b128 v[246:249], v234 offset:4672
	v_mfma_f32_32x32x16_bf16 v[66:81], v[226:229], v[146:149], 0
	s_waitcnt lgkmcnt(1)
	v_mfma_f32_32x32x16_bf16 v[82:97], v[230:233], v[134:137], v[82:97]
	ds_read_b128 v[226:229], v234 offset:4704
	v_mfma_f32_32x32x16_bf16 v[66:81], v[230:233], v[150:153], v[66:81]
	s_waitcnt lgkmcnt(1)
	v_mfma_f32_32x32x16_bf16 v[82:97], v[246:249], v[138:141], v[82:97]
	v_mfma_f32_32x32x16_bf16 v[66:81], v[246:249], v[154:157], v[66:81]
	s_waitcnt lgkmcnt(0)
	v_mfma_f32_32x32x16_bf16 v[82:97], v[226:229], v[142:145], v[82:97]
	v_mfma_f32_32x32x16_bf16 v[66:81], v[226:229], v[158:161], v[66:81]
	s_barrier
	v_exp_f32_e32 v114, v114
	v_exp_f32_e32 v115, v115
	v_exp_f32_e32 v116, v116
	v_exp_f32_e32 v117, v117
	v_exp_f32_e32 v118, v118
	v_exp_f32_e32 v119, v119
	v_exp_f32_e32 v120, v120
	v_exp_f32_e32 v121, v121
	v_cvt_pk_bf16_f32 v170, v114, v115
	v_add_f32_e32 v114, v114, v115
	v_exp_f32_e32 v122, v122
	v_exp_f32_e32 v123, v123
	v_cvt_pk_bf16_f32 v171, v116, v117
	v_add_f32_e32 v116, v116, v117
	v_add_f32_e32 v217, v217, v114
	v_exp_f32_e32 v124, v124
	v_exp_f32_e32 v125, v125
	v_cvt_pk_bf16_f32 v172, v118, v119
	v_add_f32_e32 v118, v118, v119
	v_add_f32_e32 v217, v217, v116
	v_exp_f32_e32 v126, v126
	v_exp_f32_e32 v127, v127
	v_cvt_pk_bf16_f32 v173, v120, v121
	v_add_f32_e32 v120, v120, v121
	v_add_f32_e32 v217, v217, v118
	v_exp_f32_e32 v128, v128
	v_exp_f32_e32 v129, v129
	v_cvt_pk_bf16_f32 v166, v122, v123
	v_add_f32_e32 v122, v122, v123
	v_add_f32_e32 v217, v217, v120
	v_exp_f32_e32 v98, v98
	v_exp_f32_e32 v99, v99
	v_cvt_pk_bf16_f32 v167, v124, v125
	v_add_f32_e32 v124, v124, v125
	v_add_f32_e32 v217, v217, v122
	v_exp_f32_e32 v100, v100
	v_exp_f32_e32 v101, v101
	v_cvt_pk_bf16_f32 v168, v126, v127
	v_add_f32_e32 v126, v126, v127
	v_add_f32_e32 v217, v217, v124
	v_exp_f32_e32 v102, v102
	v_exp_f32_e32 v103, v103
	v_cvt_pk_bf16_f32 v169, v128, v129
	v_add_f32_e32 v128, v128, v129
	v_add_f32_e32 v217, v217, v126
	v_exp_f32_e32 v104, v104
	v_exp_f32_e32 v105, v105
	v_cvt_pk_bf16_f32 v174, v98, v99
	v_add_f32_e32 v98, v98, v99
	v_add_f32_e32 v217, v217, v128
	v_exp_f32_e32 v106, v106
	v_exp_f32_e32 v107, v107
	v_cvt_pk_bf16_f32 v175, v100, v101
	v_add_f32_e32 v100, v100, v101
	v_add_f32_e32 v216, v216, v98
	v_exp_f32_e32 v108, v108
	v_exp_f32_e32 v109, v109
	v_cvt_pk_bf16_f32 v176, v102, v103
	v_add_f32_e32 v102, v102, v103
	v_add_f32_e32 v216, v216, v100
	v_exp_f32_e32 v110, v110
	v_exp_f32_e32 v111, v111
	v_cvt_pk_bf16_f32 v177, v104, v105
	v_add_f32_e32 v104, v104, v105
	v_add_f32_e32 v216, v216, v102
	v_exp_f32_e32 v112, v112
	v_exp_f32_e32 v113, v113
	v_cvt_pk_bf16_f32 v162, v106, v107
	v_add_f32_e32 v106, v106, v107
	v_add_f32_e32 v216, v216, v104
	v_cvt_pk_bf16_f32 v163, v108, v109
	v_add_f32_e32 v108, v108, v109
	v_add_f32_e32 v216, v216, v106
	v_cvt_pk_bf16_f32 v164, v110, v111
	v_add_f32_e32 v110, v110, v111
	v_add_f32_e32 v216, v216, v108
	v_cvt_pk_bf16_f32 v165, v112, v113
	v_add_f32_e32 v112, v112, v113
	v_add_f32_e32 v216, v216, v110
	v_add_f32_e32 v216, v216, v112
	s_waitcnt vmcnt(0)
	s_barrier
	s_cmp_eq_u32 s101, 0
	s_cbranch_scc0 .Lpp_exit
	s_barrier
